# down-projection K-loop: the eight two-step VALU address adds per iteration replaced by scalar-base loads (same edit as in-proj / gate-up)
# speedup vs baseline: 1.0066x; 1.0026x over previous
; #define PG8_STAGE(bufoff, gbase, voff) do { _Pragma("unroll") for (int _i = 0; _i < 2; ++_i) \
;         __builtin_amdgcn_global_load_lds((const unsigned*)((const char*)(gbase) + (voff)[_i]), (PG8_LAS unsigned*)(lds + (bufoff) + ldsw + _i * 8192), 16, 0, 0); } while (0)
; #define PG8_LDA(dst, b, h) do { _Pragma("unroll") for (int m = 0; m < 4; ++m) _Pragma("unroll") for (int k = 0; k < 2; ++k) dst[m][k] = *(const PG8_LAS bf16x8*)(lds + PG8_SA(b, h) + aoff + m * 2048 + k * 1024); } while (0)
; #define PG8_LDB(dst, b, h) do { _Pragma("unroll") for (int n = 0; n < 2; ++n) _Pragma("unroll") for (int k = 0; k < 2; ++k) dst[n][k] = *(const PG8_LAS bf16x8*)(lds + PG8_SB(b, h) + boff + n * 2048 + k * 1024); } while (0)
; #define PG8_WAIT_V(n) asm volatile("s_waitcnt vmcnt(" #n ")" ::: "memory")
; #define PG8_WAIT_L(n) asm volatile("s_waitcnt lgkmcnt(" #n ")" ::: "memory")
; #define PG8_BAR __builtin_amdgcn_s_barrier()
; #define PG8_SCHED __builtin_amdgcn_sched_barrier(0)
; template <class Epi, class Sched, bool ALIGN_EPI = false, bool SP2 = false>
; __device__ __forceinline__ void gemm_phase(PG8_LAS unsigned char* lds, const Gemm g, const Sched& S, const Epi& E) {
;     ...
;         const bool has_next = S.next(ui + 1, nxt);
;         const char* nA = has_next ? (const char*)g.A + (size_t)nxt.pm * tstep : cA; const char* nB = has_next ? (const char*)g.Bt + (size_t)nxt.pn * tstep : cB;
;         for (int t = 0; t < nt; t += 2) {
;             const bool last = (t == nt - 2);
;             const char* a1 = cA + (size_t)(t + 1) * kstep;
;             const char* a2 = last ? nA : cA + (size_t)(t + 2) * kstep; const char* b2 = last ? nB : cB + (size_t)(t + 2) * kstep;
;             const char* a3 = a2 + kstep; const char* b3 = b2 + kstep;
;             if (last && has_next) S.a_ready(nxt);
;             if constexpr (SP2) {
;             PG8_LDB(B0, 0, 0); PG8_LDB(B1, 0, 1); PG8_SCHED; PG8_LDA(At, 0, 0); PG8_STAGE(PG8_SA(1, 1), a1 + hstep, voffA);
;             PG8_WAIT_V(8); PG8_WAIT_L(0); PG8_BAR; PG8_MMA(0, 0, At, B0); PG8_MMA(0, 1, At, B1); PG8_BAR; PG8_SCHED;
;             PG8_LDA(At, 0, 1); PG8_STAGE(PG8_SB(0, 0), b2, voffB); PG8_STAGE(PG8_SB(0, 1), b2 + hstep, voffB); PG8_STAGE(PG8_SA(0, 0), a2, voffA);
;             PG8_WAIT_V(8); PG8_WAIT_L(0); PG8_BAR; PG8_MMA(1, 0, At, B0); PG8_MMA(1, 1, At, B1); PG8_BAR; PG8_SCHED;
.LBB0_2238:
	s_add_u32 s24, s20, 0x100
	s_addc_u32 s25, s21, 0
	s_add_i32 s30, 0, 0x10000
	s_cmpk_eq_i32 s42, 0x54
	s_cselect_b32 s37, s17, s25
	s_cselect_b32 s36, s16, s24
	s_cselect_b32 s27, s23, s41
	s_cselect_b32 s26, s22, s40
	s_add_i32 s31, 0, 0x14000
	v_add_u32_e32 v136, s30, v198
	v_add_u32_e32 v160, s31, v198
	ds_read_b128 v[124:127], v136
	ds_read_b128 v[128:131], v136 offset:1024
	ds_read_b128 v[132:135], v136 offset:2048
	ds_read_b128 v[136:139], v136 offset:3072
	ds_read_b128 v[148:151], v160
	ds_read_b128 v[152:155], v160 offset:1024
	ds_read_b128 v[156:159], v160 offset:2048
	ds_read_b128 v[160:163], v160 offset:3072
	v_lshl_add_u64 v[210:211], s[20:21], 0, v[184:185]
	s_add_i32 m0, s18, 0xc000
	ds_read_b128 v[164:167], v200
	ds_read_b128 v[168:171], v200 offset:1024
	ds_read_b128 v[172:175], v200 offset:2048
	ds_read_b128 v[186:189], v200 offset:3072
	ds_read_b128 v[190:193], v200 offset:4096
	ds_read_b128 v[194:197], v200 offset:5120
	ds_read_b128 v[202:205], v200 offset:6144
	ds_read_b128 v[206:209], v200 offset:7168
	global_load_lds_dwordx4 v[210:211], off
	v_lshl_add_u64 v[210:211], s[20:21], 0, v[182:183]
	s_add_i32 m0, s18, 0xe000
	s_nop 0
	global_load_lds_dwordx4 v[210:211], off
	s_waitcnt vmcnt(8)
	s_waitcnt lgkmcnt(0)
	s_barrier
	s_setprio 1
	s_waitcnt lgkmcnt(0)
	v_mfma_f32_16x16x32_bf16 v[144:147], v[124:127], v[164:167], v[144:147]
	v_mfma_f32_16x16x32_bf16 v[140:143], v[132:135], v[164:167], v[140:143]
	v_mfma_f32_16x16x32_bf16 v[112:115], v[124:127], v[172:175], v[112:115]
	v_mfma_f32_16x16x32_bf16 v[108:111], v[132:135], v[172:175], v[108:111]
	v_mfma_f32_16x16x32_bf16 v[100:103], v[124:127], v[190:193], v[100:103]
	v_mfma_f32_16x16x32_bf16 v[92:95], v[132:135], v[190:193], v[92:95]
	v_mfma_f32_16x16x32_bf16 v[84:87], v[124:127], v[202:205], v[84:87]
	v_mfma_f32_16x16x32_bf16 v[76:79], v[132:135], v[202:205], v[76:79]
	v_mfma_f32_16x16x32_bf16 v[144:147], v[128:131], v[168:171], v[144:147]
	v_mfma_f32_16x16x32_bf16 v[140:143], v[136:139], v[168:171], v[140:143]
	v_mfma_f32_16x16x32_bf16 v[112:115], v[128:131], v[186:189], v[112:115]
	v_mfma_f32_16x16x32_bf16 v[108:111], v[136:139], v[186:189], v[108:111]
	v_mfma_f32_16x16x32_bf16 v[100:103], v[128:131], v[194:197], v[100:103]
	v_mfma_f32_16x16x32_bf16 v[92:95], v[136:139], v[194:197], v[92:95]
	v_mfma_f32_16x16x32_bf16 v[84:87], v[128:131], v[206:209], v[84:87]
	v_mfma_f32_16x16x32_bf16 v[76:79], v[136:139], v[206:209], v[76:79]
	s_setprio 0
	s_setprio 1
	v_mfma_f32_16x16x32_bf16 v[120:123], v[148:151], v[164:167], v[120:123]
	v_mfma_f32_16x16x32_bf16 v[116:119], v[156:159], v[164:167], v[116:119]
	v_mfma_f32_16x16x32_bf16 v[104:107], v[148:151], v[172:175], v[104:107]
	v_mfma_f32_16x16x32_bf16 v[96:99], v[156:159], v[172:175], v[96:99]
	v_mfma_f32_16x16x32_bf16 v[88:91], v[148:151], v[190:193], v[88:91]
	v_mfma_f32_16x16x32_bf16 v[80:83], v[156:159], v[190:193], v[80:83]
	v_mfma_f32_16x16x32_bf16 v[72:75], v[148:151], v[202:205], v[72:75]
	v_mfma_f32_16x16x32_bf16 v[68:71], v[156:159], v[202:205], v[68:71]
	v_mfma_f32_16x16x32_bf16 v[120:123], v[152:155], v[168:171], v[120:123]
	v_mfma_f32_16x16x32_bf16 v[116:119], v[160:163], v[168:171], v[116:119]
	v_mfma_f32_16x16x32_bf16 v[104:107], v[152:155], v[186:189], v[104:107]
	v_mfma_f32_16x16x32_bf16 v[96:99], v[160:163], v[186:189], v[96:99]
	v_mfma_f32_16x16x32_bf16 v[88:91], v[152:155], v[194:197], v[88:91]
	v_mfma_f32_16x16x32_bf16 v[80:83], v[160:163], v[194:197], v[80:83]
	v_mfma_f32_16x16x32_bf16 v[72:75], v[152:155], v[206:209], v[72:75]
	v_mfma_f32_16x16x32_bf16 v[68:71], v[160:163], v[206:209], v[68:71]
	s_setprio 0
	s_barrier
	s_add_i32 s20, s30, s13
	s_mov_b32 m0, s20
	ds_read_b128 v[164:167], v200 offset:16384
	ds_read_b128 v[168:171], v200 offset:17408
	ds_read_b128 v[172:175], v200 offset:18432
	ds_read_b128 v[186:189], v200 offset:19456
	ds_read_b128 v[190:193], v200 offset:20480
	ds_read_b128 v[194:197], v200 offset:21504
	ds_read_b128 v[202:205], v200 offset:22528
	ds_read_b128 v[206:209], v200 offset:23552
	global_load_lds_dwordx4 v2, s[26:27]
	s_add_i32 m0, s20, 0x2000
	s_add_u32 s20, s26, 0x160000
	s_addc_u32 s21, s27, 0
	s_add_u32 s98, s26, s28
	s_addc_u32 s99, s27, s29
	s_add_u32 s94, s36, s28
	s_addc_u32 s95, s37, s29
	s_add_i32 s30, s31, s13
	global_load_lds_dwordx4 v180, s[26:27]
	s_mov_b32 m0, s30
	s_nop 0
	global_load_lds_dwordx4 v2, s[20:21]
	s_add_i32 m0, s30, 0x2000
	s_nop 0
	global_load_lds_dwordx4 v180, s[20:21]
	s_mov_b32 m0, s18
	s_nop 0
	global_load_lds_dwordx4 v176, s[36:37]
	s_mov_b32 m0, s44
	s_nop 0
	global_load_lds_dwordx4 v178, s[36:37]
	s_waitcnt vmcnt(8)
	s_waitcnt lgkmcnt(0)
	s_barrier
; #define PG8_STAGE(bufoff, gbase, voff) do { _Pragma("unroll") for (int _i = 0; _i < 2; ++_i) \
;         __builtin_amdgcn_global_load_lds((const unsigned*)((const char*)(gbase) + (voff)[_i]), (PG8_LAS unsigned*)(lds + (bufoff) + ldsw + _i * 8192), 16, 0, 0); } while (0)
; #define PG8_LDA(dst, b, h) do { _Pragma("unroll") for (int m = 0; m < 4; ++m) _Pragma("unroll") for (int k = 0; k < 2; ++k) dst[m][k] = *(const PG8_LAS bf16x8*)(lds + PG8_SA(b, h) + aoff + m * 2048 + k * 1024); } while (0)
; #define PG8_LDB(dst, b, h) do { _Pragma("unroll") for (int n = 0; n < 2; ++n) _Pragma("unroll") for (int k = 0; k < 2; ++k) dst[n][k] = *(const PG8_LAS bf16x8*)(lds + PG8_SB(b, h) + boff + n * 2048 + k * 1024); } while (0)
; #define PG8_MMA(ai, bj, At, Bt) do { __builtin_amdgcn_s_setprio(1); _Pragma("unroll") for (int m = 0; m < 4; ++m) _Pragma("unroll") for (int n = 0; n < 2; ++n) _Pragma("unroll") for (int k = 0; k < 2; ++k) \
;         acc[ai][bj][m][n] = __builtin_amdgcn_mfma_f32_16x16x32_bf16(Bt[n][k], At[m][k], acc[ai][bj][m][n], 0, 0, 0); __builtin_amdgcn_s_setprio(0); } while (0)
; #define PG8_WAIT_V(n) asm volatile("s_waitcnt vmcnt(" #n ")" ::: "memory")
; #define PG8_WAIT_L(n) asm volatile("s_waitcnt lgkmcnt(" #n ")" ::: "memory")
; #define PG8_BAR __builtin_amdgcn_s_barrier()
; #define PG8_SCHED __builtin_amdgcn_sched_barrier(0)
; template <class Epi, class Sched, bool ALIGN_EPI = false, bool SP2 = false>
; __device__ __forceinline__ void gemm_phase(PG8_LAS unsigned char* lds, const Gemm g, const Sched& S, const Epi& E) {
;     ...
;             PG8_WAIT_V(8); PG8_WAIT_L(0); PG8_BAR; PG8_MMA(1, 0, At, B0); PG8_MMA(1, 1, At, B1); PG8_BAR; PG8_SCHED;
;             PG8_LDB(B0, 1, 0); PG8_LDB(B1, 1, 1); PG8_SCHED; PG8_LDA(At, 1, 0); PG8_STAGE(PG8_SA(0, 1), a2 + hstep, voffA);
;             PG8_WAIT_V(8); PG8_WAIT_L(0); PG8_BAR; PG8_MMA(0, 0, At, B0); PG8_MMA(0, 1, At, B1); PG8_BAR; PG8_SCHED;
	s_setprio 1
	s_waitcnt lgkmcnt(0)
	v_mfma_f32_16x16x32_bf16 v[64:67], v[124:127], v[164:167], v[64:67]
	v_mfma_f32_16x16x32_bf16 v[60:63], v[132:135], v[164:167], v[60:63]
	v_mfma_f32_16x16x32_bf16 v[52:55], v[124:127], v[172:175], v[52:55]
	v_mfma_f32_16x16x32_bf16 v[44:47], v[132:135], v[172:175], v[44:47]
	v_mfma_f32_16x16x32_bf16 v[36:39], v[124:127], v[190:193], v[36:39]
	v_mfma_f32_16x16x32_bf16 v[28:31], v[132:135], v[190:193], v[28:31]
	v_mfma_f32_16x16x32_bf16 v[20:23], v[124:127], v[202:205], v[20:23]
	v_mfma_f32_16x16x32_bf16 v[12:15], v[132:135], v[202:205], v[12:15]
	v_mfma_f32_16x16x32_bf16 v[64:67], v[128:131], v[168:171], v[64:67]
	v_mfma_f32_16x16x32_bf16 v[60:63], v[136:139], v[168:171], v[60:63]
	v_mfma_f32_16x16x32_bf16 v[52:55], v[128:131], v[186:189], v[52:55]
	v_mfma_f32_16x16x32_bf16 v[44:47], v[136:139], v[186:189], v[44:47]
	v_mfma_f32_16x16x32_bf16 v[36:39], v[128:131], v[194:197], v[36:39]
	v_mfma_f32_16x16x32_bf16 v[28:31], v[136:139], v[194:197], v[28:31]
	v_mfma_f32_16x16x32_bf16 v[20:23], v[128:131], v[206:209], v[20:23]
	v_mfma_f32_16x16x32_bf16 v[12:15], v[136:139], v[206:209], v[12:15]
	s_setprio 0
	s_setprio 1
	v_mfma_f32_16x16x32_bf16 v[56:59], v[148:151], v[164:167], v[56:59]
	v_mfma_f32_16x16x32_bf16 v[48:51], v[156:159], v[164:167], v[48:51]
	v_mfma_f32_16x16x32_bf16 v[40:43], v[148:151], v[172:175], v[40:43]
	v_mfma_f32_16x16x32_bf16 v[32:35], v[156:159], v[172:175], v[32:35]
	v_mfma_f32_16x16x32_bf16 v[24:27], v[148:151], v[190:193], v[24:27]
	v_mfma_f32_16x16x32_bf16 v[16:19], v[156:159], v[190:193], v[16:19]
	v_mfma_f32_16x16x32_bf16 v[8:11], v[148:151], v[202:205], v[8:11]
	v_mfma_f32_16x16x32_bf16 v[4:7], v[156:159], v[202:205], v[4:7]
	v_mfma_f32_16x16x32_bf16 v[56:59], v[152:155], v[168:171], v[56:59]
	v_mfma_f32_16x16x32_bf16 v[48:51], v[160:163], v[168:171], v[48:51]
	v_mfma_f32_16x16x32_bf16 v[40:43], v[152:155], v[186:189], v[40:43]
	v_mfma_f32_16x16x32_bf16 v[32:35], v[160:163], v[186:189], v[32:35]
	v_mfma_f32_16x16x32_bf16 v[24:27], v[152:155], v[194:197], v[24:27]
	v_mfma_f32_16x16x32_bf16 v[16:19], v[160:163], v[194:197], v[16:19]
	v_mfma_f32_16x16x32_bf16 v[8:11], v[152:155], v[206:209], v[8:11]
	v_mfma_f32_16x16x32_bf16 v[4:7], v[160:163], v[206:209], v[4:7]
	s_setprio 0
	s_barrier
	s_add_i32 s30, 0, 0x18000
	s_add_i32 s31, 0, 0x1c000
	v_add_u32_e32 v136, s30, v198
	v_add_u32_e32 v160, s31, v198
	ds_read_b128 v[124:127], v136
	ds_read_b128 v[128:131], v136 offset:1024
	ds_read_b128 v[132:135], v136 offset:2048
	ds_read_b128 v[136:139], v136 offset:3072
	ds_read_b128 v[148:151], v160
	ds_read_b128 v[152:155], v160 offset:1024
	ds_read_b128 v[156:159], v160 offset:2048
	ds_read_b128 v[160:163], v160 offset:3072
	s_add_u32 s20, s36, 0x160000
	s_addc_u32 s21, s37, 0
	s_mov_b32 m0, s45
	ds_read_b128 v[164:167], v200 offset:32768
	ds_read_b128 v[168:171], v200 offset:33792
	ds_read_b128 v[172:175], v200 offset:34816
	ds_read_b128 v[186:189], v200 offset:35840
	ds_read_b128 v[190:193], v200 offset:36864
	ds_read_b128 v[194:197], v200 offset:37888
	ds_read_b128 v[202:205], v200 offset:38912
	ds_read_b128 v[206:209], v200 offset:39936
	global_load_lds_dwordx4 v176, s[20:21]
	s_mov_b32 m0, s46
	s_nop 0
	global_load_lds_dwordx4 v178, s[20:21]
	s_waitcnt vmcnt(8)
	s_waitcnt lgkmcnt(0)
	s_barrier
	s_setprio 1
	s_waitcnt lgkmcnt(0)
	v_mfma_f32_16x16x32_bf16 v[144:147], v[124:127], v[164:167], v[144:147]
	v_mfma_f32_16x16x32_bf16 v[140:143], v[132:135], v[164:167], v[140:143]
	v_mfma_f32_16x16x32_bf16 v[112:115], v[124:127], v[172:175], v[112:115]
	v_mfma_f32_16x16x32_bf16 v[108:111], v[132:135], v[172:175], v[108:111]
	v_mfma_f32_16x16x32_bf16 v[100:103], v[124:127], v[190:193], v[100:103]
	v_mfma_f32_16x16x32_bf16 v[92:95], v[132:135], v[190:193], v[92:95]
	v_mfma_f32_16x16x32_bf16 v[84:87], v[124:127], v[202:205], v[84:87]
	v_mfma_f32_16x16x32_bf16 v[76:79], v[132:135], v[202:205], v[76:79]
	v_mfma_f32_16x16x32_bf16 v[144:147], v[128:131], v[168:171], v[144:147]
	v_mfma_f32_16x16x32_bf16 v[140:143], v[136:139], v[168:171], v[140:143]
	v_mfma_f32_16x16x32_bf16 v[112:115], v[128:131], v[186:189], v[112:115]
	v_mfma_f32_16x16x32_bf16 v[108:111], v[136:139], v[186:189], v[108:111]
	v_mfma_f32_16x16x32_bf16 v[100:103], v[128:131], v[194:197], v[100:103]
	v_mfma_f32_16x16x32_bf16 v[92:95], v[136:139], v[194:197], v[92:95]
	v_mfma_f32_16x16x32_bf16 v[84:87], v[128:131], v[206:209], v[84:87]
	v_mfma_f32_16x16x32_bf16 v[76:79], v[136:139], v[206:209], v[76:79]
	s_setprio 0
	s_setprio 1
	v_mfma_f32_16x16x32_bf16 v[120:123], v[148:151], v[164:167], v[120:123]
	v_mfma_f32_16x16x32_bf16 v[116:119], v[156:159], v[164:167], v[116:119]
	v_mfma_f32_16x16x32_bf16 v[104:107], v[148:151], v[172:175], v[104:107]
	v_mfma_f32_16x16x32_bf16 v[96:99], v[156:159], v[172:175], v[96:99]
	v_mfma_f32_16x16x32_bf16 v[88:91], v[148:151], v[190:193], v[88:91]
	v_mfma_f32_16x16x32_bf16 v[80:83], v[156:159], v[190:193], v[80:83]
	v_mfma_f32_16x16x32_bf16 v[72:75], v[148:151], v[202:205], v[72:75]
	v_mfma_f32_16x16x32_bf16 v[68:71], v[156:159], v[202:205], v[68:71]
	v_mfma_f32_16x16x32_bf16 v[120:123], v[152:155], v[168:171], v[120:123]
	v_mfma_f32_16x16x32_bf16 v[116:119], v[160:163], v[168:171], v[116:119]
	v_mfma_f32_16x16x32_bf16 v[104:107], v[152:155], v[186:189], v[104:107]
	v_mfma_f32_16x16x32_bf16 v[96:99], v[160:163], v[186:189], v[96:99]
	v_mfma_f32_16x16x32_bf16 v[88:91], v[152:155], v[194:197], v[88:91]
	v_mfma_f32_16x16x32_bf16 v[80:83], v[160:163], v[194:197], v[80:83]
	v_mfma_f32_16x16x32_bf16 v[72:75], v[152:155], v[206:209], v[72:75]
	v_mfma_f32_16x16x32_bf16 v[68:71], v[160:163], v[206:209], v[68:71]
	s_setprio 0
	s_barrier
;     __device__ __forceinline__ void operator()(const f32x4 (&acc)[2][2][4][2], const Unit& u, int wr, int wc, int fr, int fq) const {
;         const int row0 = u.pm * BM + wr * 64 + fr; const int col0 = u.pn * BM + wc * 32 + 8 * fq;
;         const float* gp = gate + (size_t)((u.pm * BM) >> 12) * gstride + col0;
;         f32x4 gv[2][2];
; #pragma unroll
;         for (int bj = 0; bj < 2; ++bj)
; #pragma unroll
;             for (int n = 0; n < 2; ++n) gv[bj][n] = *(const f32x4*)(gp + bj * HALF + n * 4);
;         if (base_f32) { const float* bp = (const float*)base;
; #pragma unroll
;             for (int ai = 0; ai < 2; ++ai)
; #pragma unroll
;                 for (int m2 = 0; m2 < 2; ++m2) { f32x4 bs[2][2][2];
; #pragma unroll
;                     for (int mm = 0; mm < 2; ++mm) { const size_t off = (size_t)(row0 + ai * HALF + (2 * m2 + mm) * 16) * ldc + col0;
; #pragma unroll
;                         for (int bj = 0; bj < 2; ++bj)
; #pragma unroll
;                             for (int n = 0; n < 2; ++n) bs[mm][bj][n] = *(const f32x4*)(bp + off + bj * HALF + n * 4); }
; #pragma unroll
;                     for (int mm = 0; mm < 2; ++mm) { const size_t off = (size_t)(row0 + ai * HALF + (2 * m2 + mm) * 16) * ldc + col0;
; #pragma unroll
;                         for (int bj = 0; bj < 2; ++bj) { const f32x4 v0 = bs[mm][bj][0] + gv[bj][0] * acc[ai][bj][2 * m2 + mm][0], v1 = bs[mm][bj][1] + gv[bj][1] * acc[ai][bj][2 * m2 + mm][1];
;                             u32x4 w; w.x = cvt_pk_bf16(v0[0], v0[1]); w.y = cvt_pk_bf16(v0[2], v0[3]); w.z = cvt_pk_bf16(v1[0], v1[1]); w.w = cvt_pk_bf16(v1[2], v1[3]);
;                             *(u32x4*)(out + off + bj * HALF) = w; } }
;                     asm volatile("" ::: "memory"); }
;         } else { const bf16_t* bp = (const bf16_t*)base;
; #pragma unroll
;             for (int ai = 0; ai < 2; ++ai) { u32x4 bs[4][2];
; #pragma unroll
; template <class Epi, class Sched, bool ALIGN_EPI = false, bool SP2 = false>
; __device__ __forceinline__ void gemm_phase(PG8_LAS unsigned char* lds, const Gemm g, const Sched& S, const Epi& E) {
;     ...
;             PG8_LDA(At, 1, 1); PG8_STAGE(PG8_SB(1, 0), b3, voffB); PG8_STAGE(PG8_SB(1, 1), b3 + hstep, voffB); PG8_STAGE(PG8_SA(1, 0), a3, voffA);
;             PG8_WAIT_V(8); PG8_WAIT_L(0); PG8_BAR; PG8_MMA(1, 0, At, B0); PG8_MMA(1, 1, At, B1); PG8_BAR; PG8_SCHED;
	s_add_i32 s20, s30, s13
	s_mov_b32 m0, s20
	ds_read_b128 v[164:167], v200 offset:49152
	ds_read_b128 v[168:171], v200 offset:50176
	ds_read_b128 v[172:175], v200 offset:51200
	ds_read_b128 v[186:189], v200 offset:52224
	ds_read_b128 v[190:193], v200 offset:53248
	ds_read_b128 v[194:197], v200 offset:54272
	ds_read_b128 v[202:205], v200 offset:55296
	ds_read_b128 v[206:209], v200 offset:56320
	global_load_lds_dwordx4 v2, s[98:99]
	s_add_i32 m0, s20, 0x2000
	s_add_u32 s20, s26, 0x160080
	s_addc_u32 s21, s27, 0
	s_add_i32 s26, s31, s13
	global_load_lds_dwordx4 v180, s[98:99]
	s_mov_b32 m0, s26
	s_nop 0
	global_load_lds_dwordx4 v2, s[20:21]
	s_add_i32 m0, s26, 0x2000
	s_nop 0
	global_load_lds_dwordx4 v180, s[20:21]
	s_mov_b32 m0, s49
	s_nop 0
	global_load_lds_dwordx4 v176, s[94:95]
	s_mov_b32 m0, s50
	s_nop 0
	global_load_lds_dwordx4 v178, s[94:95]
	s_waitcnt vmcnt(8)
	s_waitcnt lgkmcnt(0)
	s_barrier
	s_setprio 1
	s_waitcnt lgkmcnt(0)
	v_mfma_f32_16x16x32_bf16 v[64:67], v[124:127], v[164:167], v[64:67]
	v_mfma_f32_16x16x32_bf16 v[60:63], v[132:135], v[164:167], v[60:63]
	v_mfma_f32_16x16x32_bf16 v[52:55], v[124:127], v[172:175], v[52:55]
	v_mfma_f32_16x16x32_bf16 v[44:47], v[132:135], v[172:175], v[44:47]
	v_mfma_f32_16x16x32_bf16 v[36:39], v[124:127], v[190:193], v[36:39]
	v_mfma_f32_16x16x32_bf16 v[28:31], v[132:135], v[190:193], v[28:31]
	v_mfma_f32_16x16x32_bf16 v[20:23], v[124:127], v[202:205], v[20:23]
	v_mfma_f32_16x16x32_bf16 v[12:15], v[132:135], v[202:205], v[12:15]
	v_mfma_f32_16x16x32_bf16 v[64:67], v[128:131], v[168:171], v[64:67]
	v_mfma_f32_16x16x32_bf16 v[60:63], v[136:139], v[168:171], v[60:63]
	v_mfma_f32_16x16x32_bf16 v[52:55], v[128:131], v[186:189], v[52:55]
	v_mfma_f32_16x16x32_bf16 v[44:47], v[136:139], v[186:189], v[44:47]
	v_mfma_f32_16x16x32_bf16 v[36:39], v[128:131], v[194:197], v[36:39]
	v_mfma_f32_16x16x32_bf16 v[28:31], v[136:139], v[194:197], v[28:31]
	v_mfma_f32_16x16x32_bf16 v[20:23], v[128:131], v[206:209], v[20:23]
	v_mfma_f32_16x16x32_bf16 v[12:15], v[136:139], v[206:209], v[12:15]
	s_setprio 0
	s_setprio 1
	v_mfma_f32_16x16x32_bf16 v[56:59], v[148:151], v[164:167], v[56:59]
	v_mfma_f32_16x16x32_bf16 v[48:51], v[156:159], v[164:167], v[48:51]
	v_mfma_f32_16x16x32_bf16 v[40:43], v[148:151], v[172:175], v[40:43]
	v_mfma_f32_16x16x32_bf16 v[32:35], v[156:159], v[172:175], v[32:35]
	v_mfma_f32_16x16x32_bf16 v[24:27], v[148:151], v[190:193], v[24:27]
	v_mfma_f32_16x16x32_bf16 v[16:19], v[156:159], v[190:193], v[16:19]
	v_mfma_f32_16x16x32_bf16 v[8:11], v[148:151], v[202:205], v[8:11]
	v_mfma_f32_16x16x32_bf16 v[4:7], v[156:159], v[202:205], v[4:7]
	v_mfma_f32_16x16x32_bf16 v[56:59], v[152:155], v[168:171], v[56:59]
	v_mfma_f32_16x16x32_bf16 v[48:51], v[160:163], v[168:171], v[48:51]
	v_mfma_f32_16x16x32_bf16 v[40:43], v[152:155], v[186:189], v[40:43]
	v_mfma_f32_16x16x32_bf16 v[32:35], v[160:163], v[186:189], v[32:35]
	v_mfma_f32_16x16x32_bf16 v[24:27], v[152:155], v[194:197], v[24:27]
	v_mfma_f32_16x16x32_bf16 v[16:19], v[160:163], v[194:197], v[16:19]
	v_mfma_f32_16x16x32_bf16 v[8:11], v[152:155], v[206:209], v[8:11]
	v_mfma_f32_16x16x32_bf16 v[4:7], v[160:163], v[206:209], v[4:7]
	s_setprio 0
	s_barrier
	s_add_i32 s42, s42, 2
	s_add_u32 s40, s40, 0x100
	s_addc_u32 s41, s41, 0
	s_cmpk_gt_u32 s42, 0x55
	s_mov_b64 s[20:21], s[24:25]
	s_cbranch_scc0 .LBB0_2238
	v_lshl_or_b32 v148, s54, 8, v199
	s_ashr_i32 s20, s33, 4
	s_mul_hi_i32 s21, s20, 0xc000
	s_mul_i32 s20, s20, 0xc000
	v_ashrrev_i32_e32 v149, 31, v148
	v_lshl_add_u32 v150, s33, 8, v1
	s_add_u32 s20, s47, s20
	v_ashrrev_i32_e32 v151, 31, v150
	v_lshlrev_b64 v[186:187], 1, v[148:149]
	s_addc_u32 s21, s48, s21
	v_lshl_add_u64 v[188:189], s[14:15], 0, v[186:187]
	v_lshlrev_b64 v[190:191], 12, v[150:151]
	v_lshl_add_u64 v[124:125], v[148:149], 2, s[20:21]
	v_lshl_add_u64 v[148:149], v[188:189], 0, v[190:191]
	flat_load_dwordx4 v[136:139], v[124:125]
	flat_load_dwordx4 v[132:135], v[124:125] offset:16
	flat_load_dwordx4 v[128:131], v[124:125] offset:512
	s_nop 0
	flat_load_dwordx4 v[124:127], v[124:125] offset:528
	s_nop 0
	flat_load_dwordx4 v[202:205], v[148:149]
	flat_load_dwordx4 v[172:175], v[148:149] offset:256
	v_or_b32_e32 v148, 16, v150
	v_ashrrev_i32_e32 v149, 31, v148
	v_lshlrev_b64 v[196:197], 12, v[148:149]
	v_lshl_add_u64 v[148:149], v[188:189], 0, v[196:197]
	flat_load_dwordx4 v[168:171], v[148:149]
	flat_load_dwordx4 v[164:167], v[148:149] offset:256
	v_or_b32_e32 v148, 32, v150
	v_ashrrev_i32_e32 v149, 31, v148
	v_lshlrev_b64 v[194:195], 12, v[148:149]
	v_lshl_add_u64 v[148:149], v[188:189], 0, v[194:195]
	flat_load_dwordx4 v[160:163], v[148:149]
	flat_load_dwordx4 v[152:155], v[148:149] offset:256
	v_or_b32_e32 v148, 48, v150
	v_ashrrev_i32_e32 v149, 31, v148
	v_lshlrev_b64 v[192:193], 12, v[148:149]
	v_lshl_add_u64 v[148:149], v[188:189], 0, v[192:193]
	flat_load_dwordx4 v[156:159], v[148:149]
	s_nop 0
	flat_load_dwordx4 v[148:151], v[148:149] offset:256
	s_mov_b64 s[20:21], 0x80000
	s_and_b64 vcc, exec, s[38:39]
	s_mov_b32 s54, s52
	s_mov_b32 s33, s53
	s_mov_b64 s[24:25], s[22:23]
	s_waitcnt vmcnt(0) lgkmcnt(0)
; __device__ __forceinline__ unsigned cvt_pk_bf16(float lo, float hi) { unsigned r; asm volatile("v_cvt_pk_bf16_f32 %0, %1, %2" : "=v"(r) : "v"(lo), "v"(hi)); return r; }
;     __device__ __forceinline__ void operator()(const f32x4 (&acc)[2][2][4][2], const Unit& u, int wr, int wc, int fr, int fq) const {
;     ...
;                 for (int m = 0; m < 4; ++m) { const size_t off = (size_t)(row0 + ai * HALF + m * 16) * ldc + col0;
; #pragma unroll
;                     for (int bj = 0; bj < 2; ++bj) { const u32x4 r = bs[m][bj]; const f32x4 a0 = acc[ai][bj][m][0], a1 = acc[ai][bj][m][1];
;                         u32x4 w;
;                         w.x = cvt_pk_bf16(__builtin_bit_cast(float, r.x << 16) + gv[bj][0][0] * a0[0], __builtin_bit_cast(float, r.x & 0xffff0000u) + gv[bj][0][1] * a0[1]);
;                         w.y = cvt_pk_bf16(__builtin_bit_cast(float, r.y << 16) + gv[bj][0][2] * a0[2], __builtin_bit_cast(float, r.y & 0xffff0000u) + gv[bj][0][3] * a0[3]);
;                         w.z = cvt_pk_bf16(__builtin_bit_cast(float, r.z << 16) + gv[bj][1][0] * a1[0], __builtin_bit_cast(float, r.z & 0xffff0000u) + gv[bj][1][1] * a1[1]);
;                         w.w = cvt_pk_bf16(__builtin_bit_cast(float, r.w << 16) + gv[bj][1][2] * a1[2], __builtin_bit_cast(float, r.w & 0xffff0000u) + gv[bj][1][3] * a1[3]);
;                         *(u32x4*)(out + off + bj * HALF) = w; } }
	v_lshlrev_b32_e32 v201, 16, v202
	v_fmac_f32_e32 v201, v144, v136
	v_and_b32_e32 v144, 0xffff0000, v202
	v_fmac_f32_e32 v144, v145, v137
	v_lshlrev_b32_e32 v145, 16, v203
	v_fmac_f32_e32 v145, v146, v138
	v_and_b32_e32 v146, 0xffff0000, v203
	v_fmac_f32_e32 v146, v147, v139
	v_cvt_pk_bf16_f32 v144, v201, v144
	v_cvt_pk_bf16_f32 v145, v145, v146
	v_lshlrev_b32_e32 v146, 16, v204
	v_fmac_f32_e32 v146, v140, v132
	v_and_b32_e32 v140, 0xffff0000, v204
	v_fmac_f32_e32 v140, v141, v133
	v_cvt_pk_bf16_f32 v146, v146, v140
	v_lshlrev_b32_e32 v140, 16, v205
	v_fmac_f32_e32 v140, v142, v134
	v_lshlrev_b32_e32 v142, 16, v172
	v_and_b32_e32 v141, 0xffff0000, v205
	v_fmac_f32_e32 v142, v120, v128
	v_and_b32_e32 v120, 0xffff0000, v172
	v_fmac_f32_e32 v141, v143, v135
	v_fmac_f32_e32 v120, v121, v129
	v_lshlrev_b32_e32 v121, 16, v173
	v_cvt_pk_bf16_f32 v147, v140, v141
	v_lshl_add_u64 v[140:141], s[14:15], 0, v[190:191]
	v_fmac_f32_e32 v121, v122, v130
	v_and_b32_e32 v122, 0xffff0000, v173
	v_lshl_add_u64 v[140:141], v[140:141], 0, v[186:187]
	v_fmac_f32_e32 v122, v123, v131
	flat_store_dwordx4 v[140:141], v[144:147]
	v_cvt_pk_bf16_f32 v120, v142, v120
	v_cvt_pk_bf16_f32 v121, v121, v122
	v_lshlrev_b32_e32 v122, 16, v174
	v_fmac_f32_e32 v122, v116, v124
	v_and_b32_e32 v116, 0xffff0000, v174
	v_fmac_f32_e32 v116, v117, v125
	v_cvt_pk_bf16_f32 v122, v122, v116
	v_lshlrev_b32_e32 v116, 16, v175
	v_fmac_f32_e32 v116, v118, v126
	v_and_b32_e32 v117, 0xffff0000, v175
	v_fmac_f32_e32 v117, v119, v127
	v_cvt_pk_bf16_f32 v123, v116, v117
	v_lshlrev_b32_e32 v116, 16, v168
	v_fmac_f32_e32 v116, v112, v136
	v_and_b32_e32 v112, 0xffff0000, v168
	v_fmac_f32_e32 v112, v113, v137
	v_lshlrev_b32_e32 v113, 16, v169
	v_fmac_f32_e32 v113, v114, v138
	v_and_b32_e32 v114, 0xffff0000, v169
	v_fmac_f32_e32 v114, v115, v139
	flat_store_dwordx4 v[140:141], v[120:123] offset:256
	v_cvt_pk_bf16_f32 v112, v116, v112
	v_cvt_pk_bf16_f32 v113, v113, v114
	v_lshlrev_b32_e32 v114, 16, v170
	v_fmac_f32_e32 v114, v108, v132
	v_and_b32_e32 v108, 0xffff0000, v170
	v_fmac_f32_e32 v108, v109, v133
	v_cvt_pk_bf16_f32 v114, v114, v108
	v_lshlrev_b32_e32 v108, 16, v171
	v_fmac_f32_e32 v108, v110, v134
	v_lshlrev_b32_e32 v110, 16, v164
	v_and_b32_e32 v109, 0xffff0000, v171
	v_fmac_f32_e32 v110, v104, v128
	v_and_b32_e32 v104, 0xffff0000, v164
	v_fmac_f32_e32 v109, v111, v135
	v_fmac_f32_e32 v104, v105, v129
	v_lshlrev_b32_e32 v105, 16, v165
	v_cvt_pk_bf16_f32 v115, v108, v109
	v_lshl_add_u64 v[108:109], s[14:15], 0, v[196:197]
	v_fmac_f32_e32 v105, v106, v130
	v_and_b32_e32 v106, 0xffff0000, v165
	v_lshl_add_u64 v[108:109], v[108:109], 0, v[186:187]
	v_fmac_f32_e32 v106, v107, v131
	flat_store_dwordx4 v[108:109], v[112:115]
	v_cvt_pk_bf16_f32 v104, v110, v104
	v_cvt_pk_bf16_f32 v105, v105, v106
	v_lshlrev_b32_e32 v106, 16, v166
	v_fmac_f32_e32 v106, v96, v124
	v_and_b32_e32 v96, 0xffff0000, v166
	v_fmac_f32_e32 v96, v97, v125
	v_cvt_pk_bf16_f32 v106, v106, v96
	v_lshlrev_b32_e32 v96, 16, v167
	v_and_b32_e32 v97, 0xffff0000, v167
	v_fmac_f32_e32 v96, v98, v126
	v_fmac_f32_e32 v97, v99, v127
	v_cvt_pk_bf16_f32 v107, v96, v97
	v_lshlrev_b32_e32 v96, 16, v160
	v_and_b32_e32 v97, 0xffff0000, v160
	v_fmac_f32_e32 v96, v100, v136
	v_fmac_f32_e32 v97, v101, v137
	flat_store_dwordx4 v[108:109], v[104:107] offset:256
	v_cvt_pk_bf16_f32 v96, v96, v97
	v_lshlrev_b32_e32 v97, 16, v161
	v_and_b32_e32 v98, 0xffff0000, v161
	v_fmac_f32_e32 v97, v102, v138
	v_fmac_f32_e32 v98, v103, v139
	v_cvt_pk_bf16_f32 v97, v97, v98
	v_lshlrev_b32_e32 v98, 16, v162
	v_fmac_f32_e32 v98, v92, v132
	v_and_b32_e32 v92, 0xffff0000, v162
	v_fmac_f32_e32 v92, v93, v133
	v_cvt_pk_bf16_f32 v98, v98, v92
	v_lshlrev_b32_e32 v92, 16, v163
	v_fmac_f32_e32 v92, v94, v134
	v_lshlrev_b32_e32 v94, 16, v152
	v_and_b32_e32 v93, 0xffff0000, v163
	v_fmac_f32_e32 v94, v88, v128
	v_and_b32_e32 v88, 0xffff0000, v152
	v_fmac_f32_e32 v93, v95, v135
	v_fmac_f32_e32 v88, v89, v129
	v_lshlrev_b32_e32 v89, 16, v153
	v_cvt_pk_bf16_f32 v99, v92, v93
	v_lshl_add_u64 v[92:93], s[14:15], 0, v[194:195]
	v_fmac_f32_e32 v89, v90, v130
	v_and_b32_e32 v90, 0xffff0000, v153
	v_lshl_add_u64 v[92:93], v[92:93], 0, v[186:187]
	v_fmac_f32_e32 v90, v91, v131
	flat_store_dwordx4 v[92:93], v[96:99]
	v_cvt_pk_bf16_f32 v88, v94, v88
	v_cvt_pk_bf16_f32 v89, v89, v90
	v_lshlrev_b32_e32 v90, 16, v154
	v_fmac_f32_e32 v90, v80, v124
	v_and_b32_e32 v80, 0xffff0000, v154
	v_fmac_f32_e32 v80, v81, v125
	v_cvt_pk_bf16_f32 v90, v90, v80
	v_lshlrev_b32_e32 v80, 16, v155
	v_and_b32_e32 v81, 0xffff0000, v155
	v_fmac_f32_e32 v80, v82, v126
	v_fmac_f32_e32 v81, v83, v127
	v_cvt_pk_bf16_f32 v91, v80, v81
	v_lshlrev_b32_e32 v80, 16, v156
	v_and_b32_e32 v81, 0xffff0000, v156
	v_fmac_f32_e32 v80, v84, v136
	v_fmac_f32_e32 v81, v85, v137
	flat_store_dwordx4 v[92:93], v[88:91] offset:256
	v_cvt_pk_bf16_f32 v80, v80, v81
	v_lshlrev_b32_e32 v81, 16, v157
	v_and_b32_e32 v82, 0xffff0000, v157
	v_fmac_f32_e32 v81, v86, v138
	v_fmac_f32_e32 v82, v87, v139
	v_cvt_pk_bf16_f32 v81, v81, v82
	v_lshlrev_b32_e32 v82, 16, v158
	v_fmac_f32_e32 v82, v76, v132
	v_and_b32_e32 v76, 0xffff0000, v158
	v_fmac_f32_e32 v76, v77, v133
	v_cvt_pk_bf16_f32 v82, v82, v76
	v_lshlrev_b32_e32 v76, 16, v159
	v_fmac_f32_e32 v76, v78, v134
	v_lshlrev_b32_e32 v78, 16, v148
	v_and_b32_e32 v77, 0xffff0000, v159
	v_fmac_f32_e32 v78, v72, v128
	v_and_b32_e32 v72, 0xffff0000, v148
	v_fmac_f32_e32 v77, v79, v135
	v_fmac_f32_e32 v72, v73, v129
	v_lshlrev_b32_e32 v73, 16, v149
	v_cvt_pk_bf16_f32 v83, v76, v77
	v_lshl_add_u64 v[76:77], s[14:15], 0, v[192:193]
	v_fmac_f32_e32 v73, v74, v130
	v_and_b32_e32 v74, 0xffff0000, v149
; __device__ __forceinline__ unsigned cvt_pk_bf16(float lo, float hi) { unsigned r; asm volatile("v_cvt_pk_bf16_f32 %0, %1, %2" : "=v"(r) : "v"(lo), "v"(hi)); return r; }
;     __device__ __forceinline__ void operator()(const f32x4 (&acc)[2][2][4][2], const Unit& u, int wr, int wc, int fr, int fq) const {
;     ...
;                 for (int m = 0; m < 4; ++m) { const size_t off = (size_t)(row0 + ai * HALF + m * 16) * ldc + col0;
; #pragma unroll
;                     for (int bj = 0; bj < 2; ++bj) bs[m][bj] = *(const u32x4*)(bp + off + bj * HALF); }
;     ...
;                 for (int m = 0; m < 4; ++m) { const size_t off = (size_t)(row0 + ai * HALF + m * 16) * ldc + col0;
; #pragma unroll
;                     for (int bj = 0; bj < 2; ++bj) { const u32x4 r = bs[m][bj]; const f32x4 a0 = acc[ai][bj][m][0], a1 = acc[ai][bj][m][1];
;                         u32x4 w;
;                         w.x = cvt_pk_bf16(__builtin_bit_cast(float, r.x << 16) + gv[bj][0][0] * a0[0], __builtin_bit_cast(float, r.x & 0xffff0000u) + gv[bj][0][1] * a0[1]);
;                         w.y = cvt_pk_bf16(__builtin_bit_cast(float, r.y << 16) + gv[bj][0][2] * a0[2], __builtin_bit_cast(float, r.y & 0xffff0000u) + gv[bj][0][3] * a0[3]);
;                         w.z = cvt_pk_bf16(__builtin_bit_cast(float, r.z << 16) + gv[bj][1][0] * a1[0], __builtin_bit_cast(float, r.z & 0xffff0000u) + gv[bj][1][1] * a1[1]);
;                         w.w = cvt_pk_bf16(__builtin_bit_cast(float, r.w << 16) + gv[bj][1][2] * a1[2], __builtin_bit_cast(float, r.w & 0xffff0000u) + gv[bj][1][3] * a1[3]);
;                         *(u32x4*)(out + off + bj * HALF) = w; } }
	v_lshl_add_u64 v[76:77], v[76:77], 0, v[186:187]
	v_fmac_f32_e32 v74, v75, v131
	flat_store_dwordx4 v[76:77], v[80:83]
	v_cvt_pk_bf16_f32 v72, v78, v72
	v_cvt_pk_bf16_f32 v73, v73, v74
	v_lshlrev_b32_e32 v74, 16, v150
	v_fmac_f32_e32 v74, v68, v124
	v_and_b32_e32 v68, 0xffff0000, v150
	v_fmac_f32_e32 v68, v69, v125
	v_cvt_pk_bf16_f32 v74, v74, v68
	v_lshlrev_b32_e32 v68, 16, v151
	v_and_b32_e32 v69, 0xffff0000, v151
	v_fmac_f32_e32 v68, v70, v126
	v_fmac_f32_e32 v69, v71, v127
	v_cvt_pk_bf16_f32 v75, v68, v69
	flat_store_dwordx4 v[76:77], v[72:75] offset:256
	v_lshl_add_u64 v[100:101], v[190:191], 0, s[20:21]
	v_lshl_add_u64 v[68:69], v[188:189], 0, v[100:101]
	flat_load_dwordx4 v[72:75], v[68:69]
	flat_load_dwordx4 v[76:79], v[68:69] offset:256
	s_mov_b64 s[20:21], 0x90000
	v_lshl_add_u64 v[102:103], v[190:191], 0, s[20:21]
	v_lshl_add_u64 v[68:69], v[188:189], 0, v[102:103]
	flat_load_dwordx4 v[80:83], v[68:69]
	flat_load_dwordx4 v[84:87], v[68:69] offset:256
	s_mov_b64 s[20:21], 0xa0000
	v_lshl_add_u64 v[104:105], v[190:191], 0, s[20:21]
	v_lshl_add_u64 v[68:69], v[188:189], 0, v[104:105]
	flat_load_dwordx4 v[88:91], v[68:69]
	flat_load_dwordx4 v[92:95], v[68:69] offset:256
	s_mov_b64 s[20:21], 0xb0000
	v_lshl_add_u64 v[106:107], v[190:191], 0, s[20:21]
	v_lshl_add_u64 v[68:69], v[188:189], 0, v[106:107]
	flat_load_dwordx4 v[96:99], v[68:69]
	s_nop 0
	flat_load_dwordx4 v[68:71], v[68:69] offset:256
	s_mov_b64 s[20:21], s[16:17]
	s_waitcnt vmcnt(0) lgkmcnt(0)
; __device__ __forceinline__ unsigned cvt_pk_bf16(float lo, float hi) { unsigned r; asm volatile("v_cvt_pk_bf16_f32 %0, %1, %2" : "=v"(r) : "v"(lo), "v"(hi)); return r; }
; #define PG8_WAIT_V(n) asm volatile("s_waitcnt vmcnt(" #n ")" ::: "memory")
; #define PG8_BAR __builtin_amdgcn_s_barrier()
;     __device__ __forceinline__ void operator()(const f32x4 (&acc)[2][2][4][2], const Unit& u, int wr, int wc, int fr, int fq) const {
;     ...
;                 for (int m = 0; m < 4; ++m) { const size_t off = (size_t)(row0 + ai * HALF + m * 16) * ldc + col0;
; #pragma unroll
;                     for (int bj = 0; bj < 2; ++bj) { const u32x4 r = bs[m][bj]; const f32x4 a0 = acc[ai][bj][m][0], a1 = acc[ai][bj][m][1];
;                         u32x4 w;
;                         w.x = cvt_pk_bf16(__builtin_bit_cast(float, r.x << 16) + gv[bj][0][0] * a0[0], __builtin_bit_cast(float, r.x & 0xffff0000u) + gv[bj][0][1] * a0[1]);
;                         w.y = cvt_pk_bf16(__builtin_bit_cast(float, r.y << 16) + gv[bj][0][2] * a0[2], __builtin_bit_cast(float, r.y & 0xffff0000u) + gv[bj][0][3] * a0[3]);
;                         w.z = cvt_pk_bf16(__builtin_bit_cast(float, r.z << 16) + gv[bj][1][0] * a1[0], __builtin_bit_cast(float, r.z & 0xffff0000u) + gv[bj][1][1] * a1[1]);
;                         w.w = cvt_pk_bf16(__builtin_bit_cast(float, r.w << 16) + gv[bj][1][2] * a1[2], __builtin_bit_cast(float, r.w & 0xffff0000u) + gv[bj][1][3] * a1[3]);
;                         *(u32x4*)(out + off + bj * HALF) = w; } }
;                 asm volatile("" ::: "memory"); }
; template <class Epi, class Sched, bool ALIGN_EPI = false, bool SP2 = false>
; __device__ __forceinline__ void gemm_phase(PG8_LAS unsigned char* lds, const Gemm g, const Sched& S, const Epi& E) {
;     ...
;         if (!has_next) break;
; #pragma unroll
;         for (int a = 0; a < 2; ++a)
; #pragma unroll
;             for (int b = 0; b < 2; ++b)
; #pragma unroll
;                 for (int m = 0; m < 4; ++m)
; #pragma unroll
;                     for (int n = 0; n < 2; ++n) acc[a][b][m][n] = (f32x4){0.f, 0.f, 0.f, 0.f};
;         cur = nxt; cA = nA; cB = nB; ++ui;
;         if constexpr (ALIGN_EPI) { if (wr == 1) PG8_BAR; }
;     }
;     PG8_WAIT_V(0);
;     if constexpr (!ALIGN_EPI) { if (wr == 0) PG8_BAR; }
;     PG8_BAR;
	v_lshlrev_b32_e32 v108, 16, v72
	v_fmac_f32_e32 v108, v64, v136
	v_and_b32_e32 v64, 0xffff0000, v72
	v_fmac_f32_e32 v64, v65, v137
	v_lshlrev_b32_e32 v65, 16, v73
	v_fmac_f32_e32 v65, v66, v138
	v_and_b32_e32 v66, 0xffff0000, v73
	v_fmac_f32_e32 v66, v67, v139
	v_cvt_pk_bf16_f32 v64, v108, v64
	v_cvt_pk_bf16_f32 v65, v65, v66
	v_lshlrev_b32_e32 v66, 16, v74
	v_fmac_f32_e32 v66, v60, v132
	v_and_b32_e32 v60, 0xffff0000, v74
	v_fmac_f32_e32 v60, v61, v133
	v_cvt_pk_bf16_f32 v66, v66, v60
	v_lshlrev_b32_e32 v60, 16, v75
	v_fmac_f32_e32 v60, v62, v134
	v_lshlrev_b32_e32 v62, 16, v76
	v_and_b32_e32 v61, 0xffff0000, v75
	v_fmac_f32_e32 v62, v56, v128
	v_and_b32_e32 v56, 0xffff0000, v76
	v_fmac_f32_e32 v61, v63, v135
	v_fmac_f32_e32 v56, v57, v129
	v_lshlrev_b32_e32 v57, 16, v77
	v_cvt_pk_bf16_f32 v67, v60, v61
	v_lshl_add_u64 v[60:61], s[14:15], 0, v[100:101]
	v_fmac_f32_e32 v57, v58, v130
	v_and_b32_e32 v58, 0xffff0000, v77
	v_lshl_add_u64 v[60:61], v[60:61], 0, v[186:187]
	v_fmac_f32_e32 v58, v59, v131
	flat_store_dwordx4 v[60:61], v[64:67]
	v_cvt_pk_bf16_f32 v56, v62, v56
	v_cvt_pk_bf16_f32 v57, v57, v58
	v_lshlrev_b32_e32 v58, 16, v78
	v_fmac_f32_e32 v58, v48, v124
	v_and_b32_e32 v48, 0xffff0000, v78
	v_fmac_f32_e32 v48, v49, v125
	v_cvt_pk_bf16_f32 v58, v58, v48
	v_lshlrev_b32_e32 v48, 16, v79
	v_and_b32_e32 v49, 0xffff0000, v79
	v_fmac_f32_e32 v48, v50, v126
	v_fmac_f32_e32 v49, v51, v127
	v_cvt_pk_bf16_f32 v59, v48, v49
	v_lshlrev_b32_e32 v48, 16, v80
	v_and_b32_e32 v49, 0xffff0000, v80
	v_fmac_f32_e32 v48, v52, v136
	v_fmac_f32_e32 v49, v53, v137
	flat_store_dwordx4 v[60:61], v[56:59] offset:256
	v_cvt_pk_bf16_f32 v48, v48, v49
	v_lshlrev_b32_e32 v49, 16, v81
	v_and_b32_e32 v50, 0xffff0000, v81
	v_fmac_f32_e32 v49, v54, v138
	v_fmac_f32_e32 v50, v55, v139
	v_cvt_pk_bf16_f32 v49, v49, v50
	v_lshlrev_b32_e32 v50, 16, v82
	v_fmac_f32_e32 v50, v44, v132
	v_and_b32_e32 v44, 0xffff0000, v82
	v_fmac_f32_e32 v44, v45, v133
	v_cvt_pk_bf16_f32 v50, v50, v44
	v_lshlrev_b32_e32 v44, 16, v83
	v_fmac_f32_e32 v44, v46, v134
	v_lshlrev_b32_e32 v46, 16, v84
	v_and_b32_e32 v45, 0xffff0000, v83
	v_fmac_f32_e32 v46, v40, v128
	v_and_b32_e32 v40, 0xffff0000, v84
	v_fmac_f32_e32 v45, v47, v135
	v_fmac_f32_e32 v40, v41, v129
	v_lshlrev_b32_e32 v41, 16, v85
	v_cvt_pk_bf16_f32 v51, v44, v45
	v_lshl_add_u64 v[44:45], s[14:15], 0, v[102:103]
	v_fmac_f32_e32 v41, v42, v130
	v_and_b32_e32 v42, 0xffff0000, v85
	v_lshl_add_u64 v[44:45], v[44:45], 0, v[186:187]
	v_fmac_f32_e32 v42, v43, v131
	flat_store_dwordx4 v[44:45], v[48:51]
	v_cvt_pk_bf16_f32 v40, v46, v40
	v_cvt_pk_bf16_f32 v41, v41, v42
	v_lshlrev_b32_e32 v42, 16, v86
	v_fmac_f32_e32 v42, v32, v124
	v_and_b32_e32 v32, 0xffff0000, v86
	v_fmac_f32_e32 v32, v33, v125
	v_cvt_pk_bf16_f32 v42, v42, v32
	v_lshlrev_b32_e32 v32, 16, v87
	v_and_b32_e32 v33, 0xffff0000, v87
	v_fmac_f32_e32 v32, v34, v126
	v_fmac_f32_e32 v33, v35, v127
	v_cvt_pk_bf16_f32 v43, v32, v33
	v_lshlrev_b32_e32 v32, 16, v88
	v_and_b32_e32 v33, 0xffff0000, v88
	v_fmac_f32_e32 v32, v36, v136
	v_fmac_f32_e32 v33, v37, v137
	flat_store_dwordx4 v[44:45], v[40:43] offset:256
	v_cvt_pk_bf16_f32 v32, v32, v33
	v_lshlrev_b32_e32 v33, 16, v89
	v_and_b32_e32 v34, 0xffff0000, v89
	v_fmac_f32_e32 v33, v38, v138
	v_fmac_f32_e32 v34, v39, v139
	v_cvt_pk_bf16_f32 v33, v33, v34
	v_lshlrev_b32_e32 v34, 16, v90
	v_fmac_f32_e32 v34, v28, v132
	v_and_b32_e32 v28, 0xffff0000, v90
	v_fmac_f32_e32 v28, v29, v133
	v_cvt_pk_bf16_f32 v34, v34, v28
	v_lshlrev_b32_e32 v28, 16, v91
	v_fmac_f32_e32 v28, v30, v134
	v_lshlrev_b32_e32 v30, 16, v92
	v_and_b32_e32 v29, 0xffff0000, v91
	v_fmac_f32_e32 v30, v24, v128
	v_and_b32_e32 v24, 0xffff0000, v92
	v_fmac_f32_e32 v29, v31, v135
	v_fmac_f32_e32 v24, v25, v129
	v_lshlrev_b32_e32 v25, 16, v93
	v_cvt_pk_bf16_f32 v35, v28, v29
	v_lshl_add_u64 v[28:29], s[14:15], 0, v[104:105]
	v_fmac_f32_e32 v25, v26, v130
	v_and_b32_e32 v26, 0xffff0000, v93
	v_lshl_add_u64 v[28:29], v[28:29], 0, v[186:187]
	v_fmac_f32_e32 v26, v27, v131
	flat_store_dwordx4 v[28:29], v[32:35]
	v_cvt_pk_bf16_f32 v24, v30, v24
	v_cvt_pk_bf16_f32 v25, v25, v26
	v_lshlrev_b32_e32 v26, 16, v94
	v_fmac_f32_e32 v26, v16, v124
	v_and_b32_e32 v16, 0xffff0000, v94
	v_fmac_f32_e32 v16, v17, v125
	v_cvt_pk_bf16_f32 v26, v26, v16
	v_lshlrev_b32_e32 v16, 16, v95
	v_and_b32_e32 v17, 0xffff0000, v95
	v_fmac_f32_e32 v16, v18, v126
	v_fmac_f32_e32 v17, v19, v127
	v_cvt_pk_bf16_f32 v27, v16, v17
	v_lshlrev_b32_e32 v16, 16, v96
	v_and_b32_e32 v17, 0xffff0000, v96
	v_fmac_f32_e32 v16, v20, v136
	v_fmac_f32_e32 v17, v21, v137
	flat_store_dwordx4 v[28:29], v[24:27] offset:256
	v_cvt_pk_bf16_f32 v16, v16, v17
	v_lshlrev_b32_e32 v17, 16, v97
	v_and_b32_e32 v18, 0xffff0000, v97
	v_fmac_f32_e32 v17, v22, v138
	v_fmac_f32_e32 v18, v23, v139
	v_cvt_pk_bf16_f32 v17, v17, v18
	v_lshlrev_b32_e32 v18, 16, v98
	v_fmac_f32_e32 v18, v12, v132
	v_and_b32_e32 v12, 0xffff0000, v98
	v_fmac_f32_e32 v12, v13, v133
	v_cvt_pk_bf16_f32 v18, v18, v12
	v_lshlrev_b32_e32 v12, 16, v99
	v_fmac_f32_e32 v12, v14, v134
	v_lshlrev_b32_e32 v14, 16, v68
	v_and_b32_e32 v13, 0xffff0000, v99
	v_fmac_f32_e32 v14, v8, v128
	v_and_b32_e32 v8, 0xffff0000, v68
	v_fmac_f32_e32 v13, v15, v135
	v_fmac_f32_e32 v8, v9, v129
	v_lshlrev_b32_e32 v9, 16, v69
	v_cvt_pk_bf16_f32 v19, v12, v13
	v_lshl_add_u64 v[12:13], s[14:15], 0, v[106:107]
	v_fmac_f32_e32 v9, v10, v130
	v_and_b32_e32 v10, 0xffff0000, v69
	v_lshl_add_u64 v[12:13], v[12:13], 0, v[186:187]
	v_fmac_f32_e32 v10, v11, v131
	flat_store_dwordx4 v[12:13], v[16:19]
	v_cvt_pk_bf16_f32 v8, v14, v8
	v_cvt_pk_bf16_f32 v9, v9, v10
	v_lshlrev_b32_e32 v10, 16, v70
	v_fmac_f32_e32 v10, v4, v124
	v_and_b32_e32 v4, 0xffff0000, v70
	v_fmac_f32_e32 v4, v5, v125
	v_cvt_pk_bf16_f32 v10, v10, v4
	v_lshlrev_b32_e32 v4, 16, v71
	v_and_b32_e32 v5, 0xffff0000, v71
	v_fmac_f32_e32 v4, v6, v126
	v_fmac_f32_e32 v5, v7, v127
	v_cvt_pk_bf16_f32 v11, v4, v5
	flat_store_dwordx4 v[12:13], v[8:11] offset:256
	s_cbranch_vccz .LBB0_2227
	s_waitcnt vmcnt(0)
	s_cmpk_gt_u32 s7, 0xff
	s_cbranch_scc1 .LBB0_2242
	s_barrier
